# P7 QK^T: odd d0 steps issue p1 before p0 so consecutive MFMAs chain on the accumulator or share the Q fragment
# speedup vs baseline: 1.0036x; 1.0036x over previous
.LBB0_734:
	s_sub_i32 s7, s72, 63
	s_cmp_gt_u32 s7, s3
	s_cbranch_scc1 .LBB0_731
	v_add_u32_e32 v1, s6, v222
	v_add_u32_e32 v2, v1, v225
	ds_read_b128 v[4:7], v2
	ds_read_b128 v[8:11], v2 offset:8192
	v_add_u32_e32 v2, v1, v224
	ds_read_b128 v[12:15], v2 offset:8192
	ds_read_b128 v[146:149], v2
	v_add_u32_e32 v2, s6, v233
	s_cmp_le_u32 s72, s1
	s_waitcnt lgkmcnt(0)
	v_mfma_f32_32x32x16_bf16 v[162:177], v[146:149], v[178:181], 0
	v_mfma_f32_32x32x16_bf16 v[146:161], v[12:15], v[178:181], 0
	v_add_u32_e32 v16, v1, v226
	ds_read_b128 v[12:15], v16
	ds_read_b128 v[238:241], v16 offset:8192
	v_mfma_f32_32x32x16_bf16 v[146:161], v[8:11], v[182:185], v[146:161]
	v_mfma_f32_32x32x16_bf16 v[162:177], v[4:7], v[182:185], v[162:177]
	v_add_u32_e32 v8, v1, v227
	ds_read_b128 v[4:7], v8
	ds_read_b128 v[8:11], v8 offset:8192
	s_waitcnt lgkmcnt(3)
	v_mfma_f32_32x32x16_bf16 v[162:177], v[12:15], v[186:189], v[162:177]
	s_waitcnt lgkmcnt(2)
	v_mfma_f32_32x32x16_bf16 v[146:161], v[238:241], v[186:189], v[146:161]
	v_add_u32_e32 v16, v1, v228
	ds_read_b128 v[12:15], v16
	ds_read_b128 v[238:241], v16 offset:8192
	s_waitcnt lgkmcnt(2)
	v_mfma_f32_32x32x16_bf16 v[146:161], v[8:11], v[190:193], v[146:161]

	v_mfma_f32_32x32x16_bf16 v[162:177], v[4:7], v[190:193], v[162:177]
	v_add_u32_e32 v8, v1, v229
	ds_read_b128 v[4:7], v8
	ds_read_b128 v[8:11], v8 offset:8192
	s_waitcnt lgkmcnt(3)
	v_mfma_f32_32x32x16_bf16 v[162:177], v[12:15], v[194:197], v[162:177]
	s_waitcnt lgkmcnt(2)
	v_mfma_f32_32x32x16_bf16 v[146:161], v[238:241], v[194:197], v[146:161]
	v_add_u32_e32 v16, v1, v230
	ds_read_b128 v[12:15], v16
	ds_read_b128 v[238:241], v16 offset:8192
	s_waitcnt lgkmcnt(2)
	v_mfma_f32_32x32x16_bf16 v[146:161], v[8:11], v[198:201], v[146:161]

	v_mfma_f32_32x32x16_bf16 v[162:177], v[4:7], v[198:201], v[162:177]
	v_add_u32_e32 v1, v1, v231
	ds_read_b128 v[4:7], v1
	ds_read_b128 v[8:11], v1 offset:8192
	s_waitcnt lgkmcnt(3)
	v_mfma_f32_32x32x16_bf16 v[162:177], v[12:15], v[202:205], v[162:177]
	s_waitcnt lgkmcnt(2)
	v_mfma_f32_32x32x16_bf16 v[146:161], v[238:241], v[202:205], v[146:161]
	s_waitcnt lgkmcnt(0)
	v_mfma_f32_32x32x16_bf16 v[146:161], v[8:11], v[206:209], v[146:161]

	v_mfma_f32_32x32x16_bf16 v[162:177], v[4:7], v[206:209], v[162:177]
	ds_read_b64_tr_b16 v[8:9], v2 offset:0
	ds_read_b64_tr_b16 v[10:11], v2 offset:0x1000
	ds_read_b64_tr_b16 v[4:5], v2 offset:0x2000
	ds_read_b64_tr_b16 v[6:7], v2 offset:0x3000
	s_cbranch_scc1 .LBB0_737
	v_cmp_gt_i32_e64 s[66:67], 26, v234
	v_cmp_gt_i32_e64 s[68:69], 27, v234
	v_cmp_gt_i32_e64 s[64:65], 25, v234
	s_and_b64 s[66:67], s[68:69], s[66:67]
	v_cmp_gt_i32_e64 s[62:63], 24, v234
	s_and_b64 s[64:65], s[66:67], s[64:65]
	v_cmp_gt_i32_e64 s[60:61], 19, v234
	s_and_b64 s[62:63], s[64:65], s[62:63]
	v_cmp_gt_i32_e64 s[58:59], 18, v234
	s_and_b64 s[60:61], s[62:63], s[60:61]
	v_cmp_gt_i32_e64 s[56:57], 17, v234
	s_and_b64 s[58:59], s[60:61], s[58:59]
	v_cmp_gt_i32_e64 s[54:55], 16, v234
	s_and_b64 s[56:57], s[58:59], s[56:57]
	v_cmp_gt_i32_e64 s[52:53], 11, v234
	s_and_b64 s[54:55], s[56:57], s[54:55]
	v_cmp_gt_i32_e64 s[50:51], 10, v234
	s_and_b64 s[52:53], s[54:55], s[52:53]
	v_cmp_gt_i32_e64 s[48:49], 9, v234
	s_and_b64 s[50:51], s[52:53], s[50:51]
	v_cmp_gt_i32_e64 s[46:47], 8, v234
	s_and_b64 s[48:49], s[50:51], s[48:49]
	v_cmp_gt_i32_e64 s[44:45], 3, v234
	s_and_b64 s[46:47], s[48:49], s[46:47]
	v_cmp_gt_i32_e64 s[42:43], 2, v234
	s_and_b64 s[44:45], s[46:47], s[44:45]
	v_cmp_gt_i32_e64 s[40:41], 1, v234
	s_and_b64 s[42:43], s[44:45], s[42:43]
	v_cmp_gt_i32_e64 s[38:39], 0, v234
	s_and_b64 s[40:41], s[42:43], s[40:41]
	s_and_b64 s[38:39], s[40:41], s[38:39]
	v_cmp_gt_i32_e64 s[34:35], 58, v234
	v_cndmask_b32_e64 v162, v162, v215, s[38:39]
	v_cmp_gt_i32_e64 s[38:39], 59, v234
	v_cmp_gt_i32_e64 s[30:31], 57, v234
	s_and_b64 s[34:35], s[38:39], s[34:35]
	v_cmp_gt_i32_e64 s[28:29], 56, v234
	s_and_b64 s[30:31], s[34:35], s[30:31]
	v_cmp_gt_i32_e64 s[26:27], 51, v234
	s_and_b64 s[28:29], s[30:31], s[28:29]
	v_cmp_gt_i32_e64 s[24:25], 50, v234
	s_and_b64 s[26:27], s[28:29], s[26:27]
	v_cmp_gt_i32_e64 s[22:23], 49, v234
	s_and_b64 s[24:25], s[26:27], s[24:25]
	v_cmp_gt_i32_e64 s[20:21], 48, v234
	s_and_b64 s[22:23], s[24:25], s[22:23]
	v_cmp_gt_i32_e64 s[18:19], 43, v234
	s_and_b64 s[20:21], s[22:23], s[20:21]
	v_cmp_gt_i32_e64 s[16:17], 42, v234
	s_and_b64 s[18:19], s[20:21], s[18:19]
	v_cmp_gt_i32_e64 s[14:15], 41, v234
	s_and_b64 s[16:17], s[18:19], s[16:17]
	v_cmp_gt_i32_e64 s[12:13], 40, v234
	s_and_b64 s[14:15], s[16:17], s[14:15]
	v_cmp_gt_i32_e64 s[10:11], 35, v234
	s_and_b64 s[12:13], s[14:15], s[12:13]
	v_cmp_gt_i32_e64 s[8:9], 34, v234
	s_and_b64 s[10:11], s[12:13], s[10:11]
	v_cmp_gt_i32_e64 s[6:7], 33, v234
	s_and_b64 s[8:9], s[10:11], s[8:9]
	v_cmp_gt_i32_e32 vcc, 32, v234
	s_and_b64 s[6:7], s[8:9], s[6:7]
	s_and_b64 vcc, s[6:7], vcc
	v_cndmask_b32_e64 v177, v177, v215, s[68:69]
	v_cndmask_b32_e64 v176, v176, v215, s[66:67]
	v_cndmask_b32_e64 v175, v175, v215, s[64:65]
	v_cndmask_b32_e64 v174, v174, v215, s[62:63]
	v_cndmask_b32_e64 v173, v173, v215, s[60:61]
	v_cndmask_b32_e64 v172, v172, v215, s[58:59]
	v_cndmask_b32_e64 v171, v171, v215, s[56:57]
	v_cndmask_b32_e64 v170, v170, v215, s[54:55]
	v_cndmask_b32_e64 v169, v169, v215, s[52:53]
	v_cndmask_b32_e64 v168, v168, v215, s[50:51]
	v_cndmask_b32_e64 v167, v167, v215, s[48:49]
	v_cndmask_b32_e64 v166, v166, v215, s[46:47]
	v_cndmask_b32_e64 v165, v165, v215, s[44:45]
	v_cndmask_b32_e64 v164, v164, v215, s[42:43]
	v_cndmask_b32_e64 v163, v163, v215, s[40:41]
	v_cndmask_b32_e64 v161, v161, v215, s[38:39]
	v_cndmask_b32_e64 v160, v160, v215, s[34:35]
	v_cndmask_b32_e64 v159, v159, v215, s[30:31]
	v_cndmask_b32_e64 v158, v158, v215, s[28:29]
	v_cndmask_b32_e64 v157, v157, v215, s[26:27]
	v_cndmask_b32_e64 v156, v156, v215, s[24:25]
	v_cndmask_b32_e64 v155, v155, v215, s[22:23]
	v_cndmask_b32_e64 v154, v154, v215, s[20:21]
	v_cndmask_b32_e64 v153, v153, v215, s[18:19]
	v_cndmask_b32_e64 v152, v152, v215, s[16:17]
	v_cndmask_b32_e64 v151, v151, v215, s[14:15]
	v_cndmask_b32_e64 v150, v150, v215, s[12:13]
	v_cndmask_b32_e64 v149, v149, v215, s[10:11]
	v_cndmask_b32_e64 v148, v148, v215, s[8:9]
	v_cndmask_b32_e64 v147, v147, v215, s[6:7]
	v_cndmask_b32_e32 v146, v146, v215, vcc

.LBB0_755:
	s_cmp_gt_i32 s0, s3
	s_cbranch_scc1 .LBB0_752
	v_add_u32_e32 v1, s6, v222
	v_add_u32_e32 v2, v1, v224
	ds_read_b128 v[4:7], v2
	ds_read_b128 v[8:11], v2 offset:8192
	v_add_u32_e32 v2, v1, v223
	ds_read_b128 v[12:15], v2 offset:8192
	ds_read_b128 v[146:149], v2
	v_add_u32_e32 v2, s6, v233
	s_add_i32 s6, s0, 63
	s_cmp_le_i32 s6, s76
	s_waitcnt lgkmcnt(0)
	v_mfma_f32_32x32x16_bf16 v[162:177], v[146:149], v[178:181], 0
	v_mfma_f32_32x32x16_bf16 v[146:161], v[12:15], v[178:181], 0
	v_add_u32_e32 v16, v1, v225
	ds_read_b128 v[12:15], v16
	ds_read_b128 v[238:241], v16 offset:8192
	v_mfma_f32_32x32x16_bf16 v[146:161], v[8:11], v[182:185], v[146:161]
	v_mfma_f32_32x32x16_bf16 v[162:177], v[4:7], v[182:185], v[162:177]
	v_add_u32_e32 v8, v1, v226
	ds_read_b128 v[4:7], v8
	ds_read_b128 v[8:11], v8 offset:8192
	s_waitcnt lgkmcnt(3)
	v_mfma_f32_32x32x16_bf16 v[162:177], v[12:15], v[186:189], v[162:177]
	s_waitcnt lgkmcnt(2)
	v_mfma_f32_32x32x16_bf16 v[146:161], v[238:241], v[186:189], v[146:161]
	v_add_u32_e32 v16, v1, v227
	ds_read_b128 v[12:15], v16
	ds_read_b128 v[238:241], v16 offset:8192
	s_waitcnt lgkmcnt(2)
	v_mfma_f32_32x32x16_bf16 v[146:161], v[8:11], v[190:193], v[146:161]

	v_mfma_f32_32x32x16_bf16 v[162:177], v[4:7], v[190:193], v[162:177]
	v_add_u32_e32 v8, v1, v229
	ds_read_b128 v[4:7], v8
	ds_read_b128 v[8:11], v8 offset:8192
	s_waitcnt lgkmcnt(3)
	v_mfma_f32_32x32x16_bf16 v[162:177], v[12:15], v[194:197], v[162:177]
	s_waitcnt lgkmcnt(2)
	v_mfma_f32_32x32x16_bf16 v[146:161], v[238:241], v[194:197], v[146:161]
	v_add_u32_e32 v16, v1, v230
	ds_read_b128 v[12:15], v16
	ds_read_b128 v[238:241], v16 offset:8192
	s_waitcnt lgkmcnt(2)
	v_mfma_f32_32x32x16_bf16 v[146:161], v[8:11], v[198:201], v[146:161]

	v_mfma_f32_32x32x16_bf16 v[162:177], v[4:7], v[198:201], v[162:177]
	v_add_u32_e32 v1, v1, v231
	ds_read_b128 v[4:7], v1
	ds_read_b128 v[8:11], v1 offset:8192
	s_waitcnt lgkmcnt(3)
	v_mfma_f32_32x32x16_bf16 v[162:177], v[12:15], v[202:205], v[162:177]
	s_waitcnt lgkmcnt(2)
	v_mfma_f32_32x32x16_bf16 v[146:161], v[238:241], v[202:205], v[146:161]
	s_waitcnt lgkmcnt(0)
	v_mfma_f32_32x32x16_bf16 v[146:161], v[8:11], v[206:209], v[146:161]

	v_mfma_f32_32x32x16_bf16 v[162:177], v[4:7], v[206:209], v[162:177]
	ds_read_b64_tr_b16 v[8:9], v2 offset:0
	ds_read_b64_tr_b16 v[10:11], v2 offset:0x1000
	ds_read_b64_tr_b16 v[4:5], v2 offset:0x2000
	ds_read_b64_tr_b16 v[6:7], v2 offset:0x3000
	s_cbranch_scc1 .LBB0_758
	v_cmp_gt_i32_e64 s[66:67], 26, v234
	v_cmp_gt_i32_e64 s[68:69], 27, v234
	v_cmp_gt_i32_e64 s[64:65], 25, v234
	s_and_b64 s[66:67], s[68:69], s[66:67]
	v_cmp_gt_i32_e64 s[62:63], 24, v234
	s_and_b64 s[64:65], s[66:67], s[64:65]
	v_cmp_gt_i32_e64 s[60:61], 19, v234
	s_and_b64 s[62:63], s[64:65], s[62:63]
	v_cmp_gt_i32_e64 s[58:59], 18, v234
	s_and_b64 s[60:61], s[62:63], s[60:61]
	v_cmp_gt_i32_e64 s[56:57], 17, v234
	s_and_b64 s[58:59], s[60:61], s[58:59]
	v_cmp_gt_i32_e64 s[54:55], 16, v234
	s_and_b64 s[56:57], s[58:59], s[56:57]
	v_cmp_gt_i32_e64 s[52:53], 11, v234
	s_and_b64 s[54:55], s[56:57], s[54:55]
	v_cmp_gt_i32_e64 s[50:51], 10, v234
	s_and_b64 s[52:53], s[54:55], s[52:53]
	v_cmp_gt_i32_e64 s[48:49], 9, v234
	s_and_b64 s[50:51], s[52:53], s[50:51]
	v_cmp_gt_i32_e64 s[46:47], 8, v234
	s_and_b64 s[48:49], s[50:51], s[48:49]
	v_cmp_gt_i32_e64 s[44:45], 3, v234
	s_and_b64 s[46:47], s[48:49], s[46:47]
	v_cmp_gt_i32_e64 s[42:43], 2, v234
	s_and_b64 s[44:45], s[46:47], s[44:45]
	v_cmp_gt_i32_e64 s[40:41], 1, v234
	s_and_b64 s[42:43], s[44:45], s[42:43]
	v_cmp_gt_i32_e64 s[38:39], 0, v234
	s_and_b64 s[40:41], s[42:43], s[40:41]
	s_and_b64 s[38:39], s[40:41], s[38:39]
	v_cmp_gt_i32_e64 s[34:35], 58, v234
	v_cndmask_b32_e64 v162, v162, v215, s[38:39]
	v_cmp_gt_i32_e64 s[38:39], 59, v234
	v_cmp_gt_i32_e64 s[30:31], 57, v234
	s_and_b64 s[34:35], s[38:39], s[34:35]
	v_cmp_gt_i32_e64 s[28:29], 56, v234
	s_and_b64 s[30:31], s[34:35], s[30:31]
	v_cmp_gt_i32_e64 s[26:27], 51, v234
	s_and_b64 s[28:29], s[30:31], s[28:29]
	v_cmp_gt_i32_e64 s[24:25], 50, v234
	s_and_b64 s[26:27], s[28:29], s[26:27]
	v_cmp_gt_i32_e64 s[22:23], 49, v234
	s_and_b64 s[24:25], s[26:27], s[24:25]
	v_cmp_gt_i32_e64 s[20:21], 48, v234
	s_and_b64 s[22:23], s[24:25], s[22:23]
	v_cmp_gt_i32_e64 s[18:19], 43, v234
	s_and_b64 s[20:21], s[22:23], s[20:21]
	v_cmp_gt_i32_e64 s[16:17], 42, v234
	s_and_b64 s[18:19], s[20:21], s[18:19]
	v_cmp_gt_i32_e64 s[14:15], 41, v234
	s_and_b64 s[16:17], s[18:19], s[16:17]
	v_cmp_gt_i32_e64 s[12:13], 40, v234
	s_and_b64 s[14:15], s[16:17], s[14:15]
	v_cmp_gt_i32_e64 s[10:11], 35, v234
	s_and_b64 s[12:13], s[14:15], s[12:13]
	v_cmp_gt_i32_e64 s[8:9], 34, v234
	s_and_b64 s[10:11], s[12:13], s[10:11]
	v_cmp_gt_i32_e64 s[6:7], 33, v234
	s_and_b64 s[8:9], s[10:11], s[8:9]
	v_cmp_gt_i32_e32 vcc, 32, v234
	s_and_b64 s[6:7], s[8:9], s[6:7]
	s_and_b64 vcc, s[6:7], vcc
	v_cndmask_b32_e64 v177, v177, v215, s[68:69]
	v_cndmask_b32_e64 v176, v176, v215, s[66:67]
	v_cndmask_b32_e64 v175, v175, v215, s[64:65]
	v_cndmask_b32_e64 v174, v174, v215, s[62:63]
	v_cndmask_b32_e64 v173, v173, v215, s[60:61]
	v_cndmask_b32_e64 v172, v172, v215, s[58:59]
	v_cndmask_b32_e64 v171, v171, v215, s[56:57]
	v_cndmask_b32_e64 v170, v170, v215, s[54:55]
	v_cndmask_b32_e64 v169, v169, v215, s[52:53]
	v_cndmask_b32_e64 v168, v168, v215, s[50:51]
	v_cndmask_b32_e64 v167, v167, v215, s[48:49]
	v_cndmask_b32_e64 v166, v166, v215, s[46:47]
	v_cndmask_b32_e64 v165, v165, v215, s[44:45]
	v_cndmask_b32_e64 v164, v164, v215, s[42:43]
	v_cndmask_b32_e64 v163, v163, v215, s[40:41]
	v_cndmask_b32_e64 v161, v161, v215, s[38:39]
	v_cndmask_b32_e64 v160, v160, v215, s[34:35]
	v_cndmask_b32_e64 v159, v159, v215, s[30:31]
	v_cndmask_b32_e64 v158, v158, v215, s[28:29]
	v_cndmask_b32_e64 v157, v157, v215, s[26:27]
	v_cndmask_b32_e64 v156, v156, v215, s[24:25]
	v_cndmask_b32_e64 v155, v155, v215, s[22:23]
	v_cndmask_b32_e64 v154, v154, v215, s[20:21]
	v_cndmask_b32_e64 v153, v153, v215, s[18:19]
	v_cndmask_b32_e64 v152, v152, v215, s[16:17]
	v_cndmask_b32_e64 v151, v151, v215, s[14:15]
	v_cndmask_b32_e64 v150, v150, v215, s[12:13]
	v_cndmask_b32_e64 v149, v149, v215, s[10:11]
	v_cndmask_b32_e64 v148, v148, v215, s[8:9]
	v_cndmask_b32_e64 v147, v147, v215, s[6:7]
	v_cndmask_b32_e32 v146, v146, v215, vcc
